# attention: QK^T MFMAs of a step permuted into two 4-long accumulate chains (5 of 6 groups)
# speedup vs baseline: 1.0033x; 1.0033x over previous
.LBB0_542:
	v_add_u32_e32 v192, s8, v212
	ds_read_b64_tr_b16 v[178:179], v192 offset:24576
	ds_read_b64_tr_b16 v[180:181], v192 offset:25088
	s_waitcnt lgkmcnt(9)
	v_mfma_f32_32x32x16_f16 v[98:113], v[174:177], v[138:141], v[34:49]
	v_add_f32_e32 v82, v66, v67
	v_add_f32_e32 v82, v68, v82
	v_add_f32_e32 v82, v69, v82
	v_add_f32_e32 v82, v70, v82
	v_add_f32_e32 v82, v71, v82
	v_cvt_pk_f16_f32 v142, v66, v67
	v_cvt_pk_f16_f32 v143, v68, v69
	ds_read_b64_tr_b16 v[174:175], v192 offset:28672
	ds_read_b64_tr_b16 v[176:177], v192 offset:29184
	v_add_f32_e32 v66, v72, v82
	s_waitcnt lgkmcnt(10)
	v_mfma_f32_32x32x16_f16 v[98:113], v[166:169], v[130:133], v[98:113]
	v_add_f32_e32 v66, v73, v66
	v_add_f32_e32 v66, v74, v66
	v_add_f32_e32 v122, v75, v66
	v_cvt_pk_f16_f32 v144, v70, v71
	v_cvt_pk_f16_f32 v145, v72, v73
	ds_read_b64_tr_b16 v[66:67], v192 offset:25600
	ds_read_b64_tr_b16 v[68:69], v192 offset:26112
	s_waitcnt lgkmcnt(11)
	v_mfma_f32_32x32x16_f16 v[98:113], v[158:161], v[118:121], v[98:113]
	v_add_f32_e32 v70, v76, v122
	v_add_f32_e32 v70, v77, v70
	v_add_f32_e32 v70, v78, v70
	v_add_f32_e32 v122, v79, v70
	v_cvt_pk_f16_f32 v134, v74, v75
	v_cvt_pk_f16_f32 v135, v76, v77
	ds_read_b64_tr_b16 v[70:71], v192 offset:29696
	ds_read_b64_tr_b16 v[72:73], v192 offset:30208
	s_waitcnt lgkmcnt(12)
	v_mfma_f32_32x32x16_f16 v[98:113], v[150:153], v[114:117], v[98:113]
	v_add_f32_e32 v74, v80, v122
	v_add_f32_e32 v74, v81, v74
	v_add_f32_e32 v74, v50, v74
	v_add_f32_e32 v122, v51, v74
	v_cvt_pk_f16_f32 v136, v78, v79
	v_cvt_pk_f16_f32 v137, v80, v81
	ds_read_b64_tr_b16 v[74:75], v192 offset:26624
	ds_read_b64_tr_b16 v[76:77], v192 offset:27136
	s_waitcnt lgkmcnt(13)
	v_mfma_f32_32x32x16_f16 v[82:97], v[170:173], v[138:141], v[34:49]
	v_add_f32_e32 v78, v52, v122
	v_add_f32_e32 v78, v53, v78
	v_add_f32_e32 v78, v54, v78
	v_add_f32_e32 v78, v55, v78
	v_cvt_pk_f16_f32 v126, v50, v51
	v_cvt_pk_f16_f32 v127, v52, v53
	ds_read_b64_tr_b16 v[50:51], v192 offset:30720
	ds_read_b64_tr_b16 v[52:53], v192 offset:31232
	s_waitcnt lgkmcnt(14)
	v_mfma_f32_32x32x16_f16 v[82:97], v[162:165], v[130:133], v[82:97]
	v_add_f32_e32 v78, v56, v78
	v_add_f32_e32 v78, v57, v78
	v_add_f32_e32 v78, v58, v78
	v_add_f32_e32 v78, v59, v78
	v_cvt_pk_f16_f32 v128, v54, v55
	v_cvt_pk_f16_f32 v129, v56, v57
	ds_read_b64_tr_b16 v[54:55], v192 offset:27648
	ds_read_b64_tr_b16 v[56:57], v192 offset:28160
	s_waitcnt lgkmcnt(14)
	v_mfma_f32_32x32x16_f16 v[82:97], v[154:157], v[118:121], v[82:97]
	v_add_f32_e32 v78, v60, v78
	v_add_f32_e32 v78, v61, v78
	v_add_f32_e32 v78, v62, v78
	v_add_f32_e32 v78, v63, v78
	v_cvt_pk_f16_f32 v122, v58, v59
	v_cvt_pk_f16_f32 v123, v60, v61
	ds_read_b64_tr_b16 v[58:59], v192 offset:31744
	ds_read_b64_tr_b16 v[60:61], v192 offset:32256
	v_mfma_f32_32x32x16_f16 v[82:97], v[146:149], v[114:117], v[82:97]
	v_add_f32_e32 v78, v64, v78
	v_add_f32_e32 v78, v65, v78
	v_add_f32_e32 v78, 0, v78
	v_cvt_pk_f16_f32 v124, v62, v63
	v_cvt_pk_f16_f32 v125, v64, v65
	v_lshl_add_u64 v[62:63], v[188:189], 0, s[54:55]
	s_add_i32 s8, s11, s76
	s_mov_b32 s9, m0
	s_mov_b32 m0, s8
	s_nop 0
	global_load_lds_dwordx4 v[62:63], off
	s_mov_b32 m0, s9
	v_lshl_add_u64 v[62:63], v[186:187], 0, s[54:55]
	s_add_i32 s8, s30, s77
	s_mov_b32 s9, m0
	s_mov_b32 m0, s8
	s_nop 0
	global_load_lds_dwordx4 v[62:63], off
	s_mov_b32 m0, s9
	v_max_f32_e32 v62, v99, v99
	v_max_f32_e32 v63, v98, v98
	v_max_f32_e32 v62, v63, v62
	v_max3_f32 v63, v100, v101, v83
	v_max3_f32 v62, v62, v82, v84
	v_max3_f32 v62, v62, v85, v102
	v_max3_f32 v63, v63, v104, v105
	v_max3_f32 v62, v62, v103, v86
	v_max3_f32 v63, v63, v88, v89
	v_max3_f32 v62, v62, v87, v106
	v_max3_f32 v63, v63, v108, v109
	v_max3_f32 v62, v62, v107, v90
	v_max3_f32 v63, v63, v92, v93
	v_max3_f32 v62, v62, v91, v110
	v_max3_f32 v63, v63, v112, v113
	v_max3_f32 v62, v62, v111, v94
	v_max3_f32 v63, v63, v96, v97
	v_max3_f32 v62, v62, v95, v63
	v_mov_b32_e32 v63, v62
	s_nop 1
	v_permlane32_swap_b32_e32 v62, v63
	v_max_f32_e32 v63, v63, v63
	v_max_f32_e32 v62, v62, v62
	v_max_f32_e32 v62, v62, v63
	v_cmp_lt_f32_e32 vcc, s81, v62
	s_cmp_lg_u64 vcc, 0
	v_add_f32_e32 v193, v214, v78
	s_cselect_b64 s[8:9], -1, 0
	s_cbranch_vccnz .LBB0_552

.LBB0_547:
	v_add_u32_e32 v194, s11, v212
	ds_read_b64_tr_b16 v[150:151], v194 offset:24576
	ds_read_b64_tr_b16 v[152:153], v194 offset:25088
	s_add_i32 s8, s30, 0x2000
	s_cmpk_lg_i32 s30, 0x4000
	s_cselect_b32 s11, s8, 0
	s_waitcnt lgkmcnt(9)
	v_mfma_f32_32x32x16_f16 v[66:81], v[62:65], v[138:141], v[34:49]
	v_add_f32_e32 v50, v98, v99
	v_add_f32_e32 v50, v100, v50
	v_add_f32_e32 v50, v101, v50
	v_add_f32_e32 v50, v102, v50
	v_add_f32_e32 v50, v103, v50
	v_cvt_pk_f16_f32 v142, v98, v99
	v_cvt_pk_f16_f32 v143, v100, v101
	ds_read_b64_tr_b16 v[154:155], v194 offset:28672
	ds_read_b64_tr_b16 v[156:157], v194 offset:29184
	v_add_f32_e32 v50, v104, v50
	v_add_f32_e32 v50, v105, v50
	v_add_f32_e32 v50, v106, v50
	v_add_f32_e32 v122, v107, v50
	s_waitcnt lgkmcnt(10)
	v_mfma_f32_32x32x16_f16 v[66:81], v[178:181], v[130:133], v[66:81]
	v_cvt_pk_f16_f32 v144, v102, v103
	v_cvt_pk_f16_f32 v145, v104, v105
	ds_read_b64_tr_b16 v[98:99], v194 offset:25600
	ds_read_b64_tr_b16 v[100:101], v194 offset:26112
	s_waitcnt lgkmcnt(11)
	v_mfma_f32_32x32x16_f16 v[66:81], v[166:169], v[118:121], v[66:81]
	v_add_f32_e32 v102, v108, v122
	v_add_f32_e32 v102, v109, v102
	v_add_f32_e32 v102, v110, v102
	v_add_f32_e32 v122, v111, v102
	v_cvt_pk_f16_f32 v134, v106, v107
	v_cvt_pk_f16_f32 v135, v108, v109
	ds_read_b64_tr_b16 v[102:103], v194 offset:29696
	ds_read_b64_tr_b16 v[104:105], v194 offset:30208
	s_waitcnt lgkmcnt(12)
	v_mfma_f32_32x32x16_f16 v[66:81], v[158:161], v[114:117], v[66:81]
	v_add_f32_e32 v106, v112, v122
	v_add_f32_e32 v106, v113, v106
	v_add_f32_e32 v106, v82, v106
	v_add_f32_e32 v122, v83, v106
	v_cvt_pk_f16_f32 v136, v110, v111
	v_cvt_pk_f16_f32 v137, v112, v113
	ds_read_b64_tr_b16 v[106:107], v194 offset:26624
	ds_read_b64_tr_b16 v[108:109], v194 offset:27136
	s_waitcnt lgkmcnt(13)
	v_mfma_f32_32x32x16_f16 v[50:65], v[174:177], v[138:141], v[34:49]
	v_add_f32_e32 v110, v84, v122
	v_add_f32_e32 v110, v85, v110
	v_add_f32_e32 v110, v86, v110
	v_add_f32_e32 v110, v87, v110
	v_cvt_pk_f16_f32 v126, v82, v83
	v_cvt_pk_f16_f32 v127, v84, v85
	ds_read_b64_tr_b16 v[82:83], v194 offset:30720
	ds_read_b64_tr_b16 v[84:85], v194 offset:31232
	s_waitcnt lgkmcnt(14)
	v_mfma_f32_32x32x16_f16 v[50:65], v[170:173], v[130:133], v[50:65]
	v_add_f32_e32 v110, v88, v110
	v_add_f32_e32 v110, v89, v110
	v_add_f32_e32 v110, v90, v110
	v_add_f32_e32 v110, v91, v110
	v_cvt_pk_f16_f32 v128, v86, v87
	v_cvt_pk_f16_f32 v129, v88, v89
	ds_read_b64_tr_b16 v[86:87], v194 offset:27648
	ds_read_b64_tr_b16 v[88:89], v194 offset:28160
	s_waitcnt lgkmcnt(14)
	v_mfma_f32_32x32x16_f16 v[50:65], v[162:165], v[118:121], v[50:65]
	v_add_f32_e32 v110, v92, v110
	v_add_f32_e32 v110, v93, v110
	v_add_f32_e32 v110, v94, v110
	v_add_f32_e32 v110, v95, v110
	v_cvt_pk_f16_f32 v122, v90, v91
	v_cvt_pk_f16_f32 v123, v92, v93
	ds_read_b64_tr_b16 v[90:91], v194 offset:31744
	ds_read_b64_tr_b16 v[92:93], v194 offset:32256
	v_mfma_f32_32x32x16_f16 v[50:65], v[146:149], v[114:117], v[50:65]
	v_add_f32_e32 v110, v96, v110
	v_add_f32_e32 v110, v97, v110
	v_add_f32_e32 v110, 0, v110
	v_cvt_pk_f16_f32 v124, v94, v95
	v_cvt_pk_f16_f32 v125, v96, v97
	v_max_f32_e32 v94, v67, v67
	v_max_f32_e32 v95, v66, v66
	v_max_f32_e32 v94, v95, v94
	s_nop 3
	v_max3_f32 v95, v68, v69, v51
	v_max3_f32 v94, v94, v50, v52
	v_max3_f32 v94, v94, v53, v70
	v_max3_f32 v95, v95, v72, v73
	v_max3_f32 v94, v94, v71, v54
	v_max3_f32 v95, v95, v56, v57
	v_max3_f32 v94, v94, v55, v74
	v_max3_f32 v95, v95, v76, v77
	v_max3_f32 v94, v94, v75, v58
	v_max3_f32 v95, v95, v60, v61
	v_max3_f32 v94, v94, v59, v78
	v_max3_f32 v95, v95, v80, v81
	v_max3_f32 v94, v94, v79, v62
	v_max3_f32 v95, v95, v64, v65
	v_max3_f32 v94, v94, v63, v95
	v_mov_b32_e32 v95, v94
	s_nop 1
	v_permlane32_swap_b32_e32 v94, v95
	v_max_f32_e32 v95, v95, v95
	v_max_f32_e32 v94, v94, v94
	s_add_i32 s8, s30, s76
	s_mov_b32 s9, m0
	s_mov_b32 m0, s8
	s_nop 0
	global_load_lds_dwordx4 v[188:189], off
	s_mov_b32 m0, s9
	v_max_f32_e32 v94, v94, v95
	s_add_i32 s8, s11, s77
	s_mov_b32 s9, m0
	s_mov_b32 m0, s8
	s_nop 0
	global_load_lds_dwordx4 v[186:187], off
	s_mov_b32 m0, s9
	v_cmp_lt_f32_e32 vcc, s81, v94
	s_cmp_lg_u64 vcc, 0
	v_add_f32_e32 v214, v193, v110
	s_cselect_b64 s[8:9], -1, 0
	s_cbranch_vccnz .LBB0_555

; __device__ __forceinline__ void cmask(f32x16& p0, f32x16& p1, int jb, int qrel, int hi) {
;     const float NEG = -INFINITY; int kb = 64 * jb + 4 * hi;
; #pragma unroll
;     for (int r = 0; r < 16; ++r) { int kv = kb + (r & 3) + 8 * (r >> 2); if (kv > qrel) p0[r] = NEG; if (kv + 32 > qrel) p1[r] = NEG; }
; }
.LBB0_560:
	v_add_u32_e32 v112, s68, v212
	ds_read_b64_tr_b16 v[98:99], v112 offset:24576
	ds_read_b64_tr_b16 v[100:101], v112 offset:25088
	v_add_f32_e32 v82, v66, v67
	v_add_f32_e32 v82, v68, v82
	v_add_f32_e32 v82, v69, v82
	v_add_f32_e32 v82, v70, v82
	v_add_f32_e32 v102, v71, v82
	s_waitcnt lgkmcnt(9)
	v_mfma_f32_32x32x16_f16 v[82:97], v[174:177], v[138:141], v[34:49]
	v_cvt_pk_f16_f32 v142, v66, v67
	v_cvt_pk_f16_f32 v143, v68, v69
	ds_read_b64_tr_b16 v[66:67], v112 offset:28672
	ds_read_b64_tr_b16 v[68:69], v112 offset:29184
	s_waitcnt lgkmcnt(10)
	v_mfma_f32_32x32x16_f16 v[82:97], v[166:169], v[130:133], v[82:97]
	v_add_f32_e32 v102, v72, v102
	v_add_f32_e32 v102, v73, v102
	v_add_f32_e32 v102, v74, v102
	v_add_f32_e32 v102, v75, v102
	v_cvt_pk_f16_f32 v144, v70, v71
	v_cvt_pk_f16_f32 v145, v72, v73
	ds_read_b64_tr_b16 v[70:71], v112 offset:25600
	ds_read_b64_tr_b16 v[72:73], v112 offset:26112
	s_waitcnt lgkmcnt(11)
	v_mfma_f32_32x32x16_f16 v[82:97], v[158:161], v[118:121], v[82:97]
	v_add_f32_e32 v102, v76, v102
	v_add_f32_e32 v102, v77, v102
	v_add_f32_e32 v102, v78, v102
	v_add_f32_e32 v102, v79, v102
	v_cvt_pk_f16_f32 v134, v74, v75
	v_cvt_pk_f16_f32 v135, v76, v77
	ds_read_b64_tr_b16 v[74:75], v112 offset:29696
	ds_read_b64_tr_b16 v[76:77], v112 offset:30208
	s_waitcnt lgkmcnt(12)
	v_mfma_f32_32x32x16_f16 v[82:97], v[150:153], v[114:117], v[82:97]
	v_add_f32_e32 v102, v80, v102
	v_add_f32_e32 v102, v81, v102
	v_add_f32_e32 v102, v50, v102
	v_add_f32_e32 v102, v51, v102
	v_cvt_pk_f16_f32 v136, v78, v79
	v_cvt_pk_f16_f32 v137, v80, v81
	ds_read_b64_tr_b16 v[78:79], v112 offset:26624
	ds_read_b64_tr_b16 v[80:81], v112 offset:27136
	s_waitcnt lgkmcnt(13)
	v_mfma_f32_32x32x16_f16 v[34:49], v[170:173], v[138:141], v[34:49]
	v_add_f32_e32 v102, v52, v102
	v_add_f32_e32 v102, v53, v102
	v_add_f32_e32 v102, v54, v102
	v_add_f32_e32 v106, v55, v102
	v_cvt_pk_f16_f32 v126, v50, v51
	v_cvt_pk_f16_f32 v127, v52, v53
	ds_read_b64_tr_b16 v[102:103], v112 offset:30720
	ds_read_b64_tr_b16 v[104:105], v112 offset:31232
	s_waitcnt lgkmcnt(14)
	v_mfma_f32_32x32x16_f16 v[34:49], v[162:165], v[130:133], v[34:49]
	v_add_f32_e32 v50, v56, v106
	v_add_f32_e32 v50, v57, v50
	v_add_f32_e32 v50, v58, v50
	v_add_f32_e32 v50, v59, v50
	v_cvt_pk_f16_f32 v128, v54, v55
	v_cvt_pk_f16_f32 v129, v56, v57
	ds_read_b64_tr_b16 v[106:107], v112 offset:27648
	ds_read_b64_tr_b16 v[108:109], v112 offset:28160
	s_waitcnt lgkmcnt(14)
	v_mfma_f32_32x32x16_f16 v[34:49], v[154:157], v[118:121], v[34:49]
	v_add_f32_e32 v50, v60, v50
	v_add_f32_e32 v50, v61, v50
	v_add_f32_e32 v50, v62, v50
	v_add_f32_e32 v50, v63, v50
	v_cvt_pk_f16_f32 v122, v58, v59
	v_cvt_pk_f16_f32 v123, v60, v61
	ds_read_b64_tr_b16 v[110:111], v112 offset:31744
	ds_read_b64_tr_b16 v[112:113], v112 offset:32256
	v_mfma_f32_32x32x16_f16 v[34:49], v[146:149], v[114:117], v[34:49]
	v_add_f32_e32 v50, v64, v50
	v_add_f32_e32 v50, v65, v50
	v_add_f32_e32 v50, 0, v50
	v_cvt_pk_f16_f32 v124, v62, v63
	v_cvt_pk_f16_f32 v125, v64, v65
	s_cmp_gt_i32 s29, 7
	s_cbranch_scc1 .LBB0_562
	v_mov_b32_e32 v51, v190
	v_or_b32_e32 v53, 0xe0, v208
	v_add_u32_e32 v51, s89, v51
	v_or_b32_e32 v52, 0xc0, v208
	v_cmp_le_i32_e32 vcc, v53, v51
	s_nop 1
	v_cndmask_b32_e32 v34, v200, v34, vcc
	v_cmp_lt_i32_e32 vcc, v52, v51
	s_nop 1
	v_cndmask_b32_e32 v83, v200, v83, vcc
	v_cmp_le_i32_e32 vcc, v52, v51
	v_or_b32_e32 v52, 0xe1, v208
	s_nop 0
	v_cndmask_b32_e32 v82, v200, v82, vcc
	v_cmp_le_i32_e32 vcc, v52, v51
	v_or_b32_e32 v52, 0xc2, v208
	s_nop 0
	v_cndmask_b32_e32 v35, v200, v35, vcc
	v_cmp_le_i32_e32 vcc, v52, v51
	v_or_b32_e32 v52, 0xe2, v208
	s_nop 0
	v_cndmask_b32_e32 v84, v200, v84, vcc
	v_cmp_le_i32_e32 vcc, v52, v51
	v_or_b32_e32 v52, 0xc3, v208
	s_nop 0
	v_cndmask_b32_e32 v36, v200, v36, vcc
	v_cmp_le_i32_e32 vcc, v52, v51
	v_or_b32_e32 v52, 0xe3, v208
	s_nop 0
	v_cndmask_b32_e32 v85, v200, v85, vcc
	v_cmp_le_i32_e32 vcc, v52, v51
	v_or_b32_e32 v52, 0xc8, v208
	s_nop 0
	v_cndmask_b32_e32 v37, v200, v37, vcc
	v_cmp_le_i32_e32 vcc, v52, v51
	v_or_b32_e32 v52, 0xe8, v208
	s_nop 0
	v_cndmask_b32_e32 v86, v200, v86, vcc
	v_cmp_le_i32_e32 vcc, v52, v51
	v_or_b32_e32 v52, 0xc9, v208
	s_nop 0
	v_cndmask_b32_e32 v38, v200, v38, vcc
	v_cmp_le_i32_e32 vcc, v52, v51
	v_or_b32_e32 v52, 0xe9, v208
	s_nop 0
	v_cndmask_b32_e32 v87, v200, v87, vcc
	v_cmp_le_i32_e32 vcc, v52, v51
	v_or_b32_e32 v52, 0xca, v208
	s_nop 0
	v_cndmask_b32_e32 v39, v200, v39, vcc
	v_cmp_le_i32_e32 vcc, v52, v51
	v_or_b32_e32 v52, 0xea, v208
	s_nop 0
	v_cndmask_b32_e32 v88, v200, v88, vcc
	v_cmp_le_i32_e32 vcc, v52, v51
	v_or_b32_e32 v52, 0xcb, v208
	s_nop 0
	v_cndmask_b32_e32 v40, v200, v40, vcc
	v_cmp_le_i32_e32 vcc, v52, v51
	v_or_b32_e32 v52, 0xeb, v208
	s_nop 0
	v_cndmask_b32_e32 v89, v200, v89, vcc
	v_cmp_le_i32_e32 vcc, v52, v51
	v_or_b32_e32 v52, 0xd0, v208
	s_nop 0
	v_cndmask_b32_e32 v41, v200, v41, vcc
	v_cmp_le_i32_e32 vcc, v52, v51
	v_or_b32_e32 v52, 0xf0, v208
	s_nop 0
	v_cndmask_b32_e32 v90, v200, v90, vcc
	v_cmp_le_i32_e32 vcc, v52, v51
	v_or_b32_e32 v52, 0xd1, v208
	s_nop 0
	v_cndmask_b32_e32 v42, v200, v42, vcc
	v_cmp_le_i32_e32 vcc, v52, v51
	v_or_b32_e32 v52, 0xf1, v208
	s_nop 0
	v_cndmask_b32_e32 v91, v200, v91, vcc
	v_cmp_le_i32_e32 vcc, v52, v51
	v_or_b32_e32 v52, 0xd2, v208
	s_nop 0
	v_cndmask_b32_e32 v43, v200, v43, vcc
	v_cmp_le_i32_e32 vcc, v52, v51
	v_or_b32_e32 v52, 0xf2, v208
	s_nop 0
	v_cndmask_b32_e32 v92, v200, v92, vcc
	v_cmp_le_i32_e32 vcc, v52, v51
	v_or_b32_e32 v52, 0xd3, v208
	s_nop 0
	v_cndmask_b32_e32 v44, v200, v44, vcc
	v_cmp_le_i32_e32 vcc, v52, v51
	v_or_b32_e32 v52, 0xf3, v208
	s_nop 0
	v_cndmask_b32_e32 v93, v200, v93, vcc
	v_cmp_le_i32_e32 vcc, v52, v51
	v_or_b32_e32 v52, 0xd8, v208
	s_nop 0
	v_cndmask_b32_e32 v45, v200, v45, vcc
	v_cmp_le_i32_e32 vcc, v52, v51
	v_or_b32_e32 v52, 0xf8, v208
	s_nop 0
	v_cndmask_b32_e32 v94, v200, v94, vcc
	v_cmp_le_i32_e32 vcc, v52, v51
	v_or_b32_e32 v52, 0xd9, v208
	s_nop 0
	v_cndmask_b32_e32 v46, v200, v46, vcc
	v_cmp_le_i32_e32 vcc, v52, v51
	v_or_b32_e32 v52, 0xf9, v208
	s_nop 0
	v_cndmask_b32_e32 v95, v200, v95, vcc
	v_cmp_le_i32_e32 vcc, v52, v51
	v_or_b32_e32 v52, 0xda, v208
	s_nop 0
	v_cndmask_b32_e32 v47, v200, v47, vcc
	v_cmp_le_i32_e32 vcc, v52, v51
	v_or_b32_e32 v52, 0xfa, v208
	s_nop 0
	v_cndmask_b32_e32 v96, v200, v96, vcc
	v_cmp_le_i32_e32 vcc, v52, v51
	v_or_b32_e32 v52, 0xdb, v208
	s_nop 0
	v_cndmask_b32_e32 v48, v200, v48, vcc
	v_cmp_le_i32_e32 vcc, v52, v51
	v_or_b32_e32 v52, 0xfb, v208
	s_nop 0
	v_cndmask_b32_e32 v97, v200, v97, vcc
	v_cmp_le_i32_e32 vcc, v52, v51
	s_nop 1
	v_cndmask_b32_e32 v49, v200, v49, vcc

.LBB0_571:
	v_add_u32_e32 v182, s30, v212
	ds_read_b64_tr_b16 v[178:179], v182 offset:24576
	ds_read_b64_tr_b16 v[180:181], v182 offset:25088
	s_waitcnt lgkmcnt(9)
	v_mfma_f32_32x32x16_f16 v[98:113], v[174:177], v[138:141], v[34:49]
	v_add_f32_e32 v82, v66, v67
	v_add_f32_e32 v82, v68, v82
	v_add_f32_e32 v82, v69, v82
	v_add_f32_e32 v82, v70, v82
	v_add_f32_e32 v82, v71, v82
	v_cvt_pk_f16_f32 v142, v66, v67
	v_cvt_pk_f16_f32 v143, v68, v69
	ds_read_b64_tr_b16 v[174:175], v182 offset:28672
	ds_read_b64_tr_b16 v[176:177], v182 offset:29184
	v_add_f32_e32 v66, v72, v82
	s_waitcnt lgkmcnt(10)
	v_mfma_f32_32x32x16_f16 v[98:113], v[166:169], v[130:133], v[98:113]
	v_add_f32_e32 v66, v73, v66
	v_add_f32_e32 v66, v74, v66
	v_add_f32_e32 v122, v75, v66
	v_cvt_pk_f16_f32 v144, v70, v71
	v_cvt_pk_f16_f32 v145, v72, v73
	ds_read_b64_tr_b16 v[66:67], v182 offset:25600
	ds_read_b64_tr_b16 v[68:69], v182 offset:26112
	s_waitcnt lgkmcnt(11)
	v_mfma_f32_32x32x16_f16 v[98:113], v[158:161], v[118:121], v[98:113]
	v_add_f32_e32 v70, v76, v122
	v_add_f32_e32 v70, v77, v70
	v_add_f32_e32 v70, v78, v70
	v_add_f32_e32 v122, v79, v70
	v_cvt_pk_f16_f32 v134, v74, v75
	v_cvt_pk_f16_f32 v135, v76, v77
	ds_read_b64_tr_b16 v[70:71], v182 offset:29696
	ds_read_b64_tr_b16 v[72:73], v182 offset:30208
	s_waitcnt lgkmcnt(12)
	v_mfma_f32_32x32x16_f16 v[98:113], v[150:153], v[114:117], v[98:113]
	v_add_f32_e32 v74, v80, v122
	v_add_f32_e32 v74, v81, v74
	v_add_f32_e32 v74, v50, v74
	v_add_f32_e32 v122, v51, v74
	v_cvt_pk_f16_f32 v136, v78, v79
	v_cvt_pk_f16_f32 v137, v80, v81
	ds_read_b64_tr_b16 v[74:75], v182 offset:26624
	ds_read_b64_tr_b16 v[76:77], v182 offset:27136
	s_waitcnt lgkmcnt(13)
	v_mfma_f32_32x32x16_f16 v[82:97], v[170:173], v[138:141], v[34:49]
	v_add_f32_e32 v78, v52, v122
	v_add_f32_e32 v78, v53, v78
	v_add_f32_e32 v78, v54, v78
	v_add_f32_e32 v78, v55, v78
	v_cvt_pk_f16_f32 v126, v50, v51
	v_cvt_pk_f16_f32 v127, v52, v53
	ds_read_b64_tr_b16 v[50:51], v182 offset:30720
	ds_read_b64_tr_b16 v[52:53], v182 offset:31232
	s_waitcnt lgkmcnt(14)
	v_mfma_f32_32x32x16_f16 v[82:97], v[162:165], v[130:133], v[82:97]
	v_add_f32_e32 v78, v56, v78
	v_add_f32_e32 v78, v57, v78
	v_add_f32_e32 v78, v58, v78
	v_add_f32_e32 v78, v59, v78
	v_cvt_pk_f16_f32 v128, v54, v55
	v_cvt_pk_f16_f32 v129, v56, v57
	ds_read_b64_tr_b16 v[54:55], v182 offset:27648
	ds_read_b64_tr_b16 v[56:57], v182 offset:28160
	s_waitcnt lgkmcnt(14)
	v_mfma_f32_32x32x16_f16 v[82:97], v[154:157], v[118:121], v[82:97]
	v_add_f32_e32 v78, v60, v78
	v_add_f32_e32 v78, v61, v78
	v_add_f32_e32 v78, v62, v78
	v_add_f32_e32 v78, v63, v78
	v_cvt_pk_f16_f32 v122, v58, v59
	v_cvt_pk_f16_f32 v123, v60, v61
	ds_read_b64_tr_b16 v[58:59], v182 offset:31744
	ds_read_b64_tr_b16 v[60:61], v182 offset:32256
	v_mfma_f32_32x32x16_f16 v[82:97], v[146:149], v[114:117], v[82:97]
	v_add_f32_e32 v78, v64, v78
	v_add_f32_e32 v78, v65, v78
	v_add_f32_e32 v78, 0, v78
	v_cvt_pk_f16_f32 v124, v62, v63
	v_cvt_pk_f16_f32 v125, v64, v65
	s_add_i32 s4, s40, 3
	s_cmp_ge_u32 s4, s35
	s_cselect_b64 s[70:71], -1, 0
	s_and_b64 vcc, exec, s[70:71]
	s_cbranch_vccnz .LBB0_573
	v_lshl_add_u64 v[62:63], v[194:195], 0, s[54:55]
	s_add_i32 s4, s11, s76
	s_mov_b32 s5, m0
	s_mov_b32 m0, s4
	s_nop 0
	global_load_lds_dwordx4 v[62:63], off
	s_mov_b32 m0, s5

.LBB0_587:
	v_add_u32_e32 v216, s11, v212
	ds_read_b64_tr_b16 v[186:187], v216 offset:24576
	ds_read_b64_tr_b16 v[188:189], v216 offset:25088
	s_waitcnt lgkmcnt(9)
	v_mfma_f32_32x32x16_f16 v[66:81], v[174:177], v[138:141], v[34:49]
	v_add_f32_e32 v50, v98, v99
	v_add_f32_e32 v50, v100, v50
	v_add_f32_e32 v50, v101, v50
	v_add_f32_e32 v50, v102, v50
	v_add_f32_e32 v50, v103, v50
	v_cvt_pk_f16_f32 v142, v98, v99
	v_cvt_pk_f16_f32 v143, v100, v101
	ds_read_b64_tr_b16 v[182:183], v216 offset:28672
	ds_read_b64_tr_b16 v[184:185], v216 offset:29184
	v_add_f32_e32 v50, v104, v50
	v_add_f32_e32 v50, v105, v50
	v_add_f32_e32 v50, v106, v50
	v_add_f32_e32 v98, v107, v50
	s_waitcnt lgkmcnt(10)
	v_mfma_f32_32x32x16_f16 v[66:81], v[166:169], v[130:133], v[66:81]
	v_cvt_pk_f16_f32 v144, v102, v103
	v_cvt_pk_f16_f32 v145, v104, v105
	ds_read_b64_tr_b16 v[178:179], v216 offset:25600
	ds_read_b64_tr_b16 v[180:181], v216 offset:26112
	s_waitcnt lgkmcnt(11)
	v_mfma_f32_32x32x16_f16 v[66:81], v[158:161], v[118:121], v[66:81]
	v_add_f32_e32 v98, v108, v98
	v_add_f32_e32 v98, v109, v98
	v_add_f32_e32 v98, v110, v98
	v_add_f32_e32 v98, v111, v98
	v_cvt_pk_f16_f32 v134, v106, v107
	v_cvt_pk_f16_f32 v135, v108, v109
	ds_read_b64_tr_b16 v[106:107], v216 offset:29696
	ds_read_b64_tr_b16 v[108:109], v216 offset:30208
	s_waitcnt lgkmcnt(12)
	v_mfma_f32_32x32x16_f16 v[66:81], v[150:153], v[114:117], v[66:81]
	v_add_f32_e32 v98, v112, v98
	v_add_f32_e32 v98, v113, v98
	v_add_f32_e32 v98, v82, v98
	v_add_f32_e32 v98, v83, v98
	v_cvt_pk_f16_f32 v136, v110, v111
	v_cvt_pk_f16_f32 v137, v112, v113
	ds_read_b64_tr_b16 v[102:103], v216 offset:26624
	ds_read_b64_tr_b16 v[104:105], v216 offset:27136
	s_waitcnt lgkmcnt(13)
	v_mfma_f32_32x32x16_f16 v[50:65], v[170:173], v[138:141], v[34:49]
	v_add_f32_e32 v98, v84, v98
	v_add_f32_e32 v98, v85, v98
	v_add_f32_e32 v98, v86, v98
	v_add_f32_e32 v110, v87, v98
	v_cvt_pk_f16_f32 v126, v82, v83
	v_cvt_pk_f16_f32 v127, v84, v85
	ds_read_b64_tr_b16 v[98:99], v216 offset:30720
	ds_read_b64_tr_b16 v[100:101], v216 offset:31232
	s_waitcnt lgkmcnt(14)
	v_mfma_f32_32x32x16_f16 v[50:65], v[162:165], v[130:133], v[50:65]
	v_add_f32_e32 v82, v88, v110
	v_add_f32_e32 v82, v89, v82
	v_add_f32_e32 v82, v90, v82
	v_add_f32_e32 v82, v91, v82
	v_cvt_pk_f16_f32 v128, v86, v87
	v_cvt_pk_f16_f32 v129, v88, v89
	ds_read_b64_tr_b16 v[86:87], v216 offset:27648
	ds_read_b64_tr_b16 v[88:89], v216 offset:28160
	s_waitcnt lgkmcnt(14)
	v_mfma_f32_32x32x16_f16 v[50:65], v[154:157], v[118:121], v[50:65]
	v_add_f32_e32 v82, v92, v82
	v_add_f32_e32 v82, v93, v82
	v_add_f32_e32 v82, v94, v82
	v_add_f32_e32 v110, v95, v82
	v_cvt_pk_f16_f32 v122, v90, v91
	v_cvt_pk_f16_f32 v123, v92, v93
	ds_read_b64_tr_b16 v[82:83], v216 offset:31744
	ds_read_b64_tr_b16 v[84:85], v216 offset:32256
	v_mfma_f32_32x32x16_f16 v[50:65], v[146:149], v[114:117], v[50:65]
	v_add_f32_e32 v90, v96, v110
	v_add_f32_e32 v90, v97, v90
	v_add_f32_e32 v90, 0, v90
	v_cvt_pk_f16_f32 v124, v94, v95
	v_cvt_pk_f16_f32 v125, v96, v97
	s_add_i32 s5, s40, 4
	s_cmp_ge_u32 s5, s35
	s_cselect_b64 s[30:31], -1, 0
	s_and_b64 vcc, exec, s[30:31]
	s_cbranch_vccnz .LBB0_589
	s_add_i32 s5, s68, s76
	s_mov_b32 s8, m0
	s_mov_b32 m0, s5
	s_nop 0
	global_load_lds_dwordx4 v[194:195], off
	s_mov_b32 m0, s8
